# G3 units: the 16 LDS fragment reads of the (peeled) first load segment issued at the top of the unit loop so the next-unit scalar index computation runs in their shadow; stacked on stack29
# baseline (speedup 1.0000x reference)
;     __host__ __device__ bool next(int i, Unit& u) const {
;         const long L = (long)i * G + c; if (L >= nwg) return false;
;         int wgid = (int)L; { const int q = nwg / NXCD, r = nwg % NXCD, xcd = wgid % NXCD, off = wgid / NXCD; wgid = (xcd < r ? xcd * (q + 1) : r * (q + 1) + (xcd - r) * q) + off; }
;         const int nig = WGM * nN, gid = wgid / nig, fm = gid * WGM, gsz = (nM - fm) < WGM ? (nM - fm) : WGM;
;         u.pm = fm + ((wgid % nig) % gsz); u.pn = (wgid % nig) / gsz; return true;
; template <class Epi, class Sched, bool ALIGN_EPI = false, bool SP2 = false>
; __device__ __forceinline__ void gemm_phase(PG8_LAS unsigned char* lds, const Gemm g, const Sched& S, const Epi& E) {
;     ...
;         const bool has_next = S.next(ui + 1, nxt);
.LBB0_810:
	v_add_u32_e32 v156, 0x10000, v145
	v_add_u32_e32 v172, 0x14000, v145
	ds_read_b128 v[140:143], v156
	ds_read_b128 v[148:151], v156 offset:1024
	ds_read_b128 v[152:155], v156 offset:2048
	ds_read_b128 v[156:159], v156 offset:3072
	ds_read_b128 v[160:163], v172
	ds_read_b128 v[164:167], v172 offset:1024
	ds_read_b128 v[168:171], v172 offset:2048
	ds_read_b128 v[172:175], v172 offset:3072
	ds_read_b128 v[176:179], v147
	ds_read_b128 v[180:183], v147 offset:1024
	ds_read_b128 v[184:187], v147 offset:2048
	ds_read_b128 v[188:191], v147 offset:3072
	ds_read_b128 v[192:195], v147 offset:4096
	ds_read_b128 v[196:199], v147 offset:5120
	ds_read_b128 v[200:203], v147 offset:6144
	ds_read_b128 v[204:207], v147 offset:7168
	s_add_i32 s25, s25, 1
	s_mul_i32 s28, s25, s56
	s_mul_hi_u32 s8, s25, s56
	s_add_u32 s36, s28, s24
	s_addc_u32 s37, s8, s3
	v_mov_b64_e32 v[0:1], 0xb00
	v_cmp_lt_i64_e64 s[38:39], s[36:37], v[0:1]
	v_mov_b64_e32 v[0:1], 0xaff
	v_cmp_gt_i64_e32 vcc, s[36:37], v[0:1]
	s_cbranch_vccnz .LBB0_812
	s_ashr_i32 s8, s36, 31
	s_lshr_b32 s8, s8, 29
	s_add_i32 s8, s36, s8
	s_ashr_i32 s28, s8, 3
	s_and_b32 s8, s8, -8
	s_sub_i32 s8, s36, s8
	s_cmp_lt_i32 s8, 0
	s_movk_i32 s29, 0x161
	s_cselect_b32 s29, s29, 0x160
	s_mul_i32 s8, s8, s29
	s_add_i32 s8, s8, s28
	s_mul_hi_i32 s28, s8, 0x2e8ba2e9
	s_lshr_b32 s29, s28, 31
	s_ashr_i32 s28, s28, 4
	s_add_i32 s28, s28, s29
	s_lshl_b32 s29, s28, 2
	s_mulk_i32 s28, 0x58
	s_sub_i32 s8, s8, s28
	s_bfe_i32 s28, s8, 0x80000
	s_bfe_u32 s28, s28, 0x2000d
	s_add_i32 s28, s8, s28
	s_and_b32 s30, s28, 0xfc
	s_sub_i32 s8, s8, s30
	s_sext_i32_i8 s8, s8
	s_add_i32 s48, s29, s8
	s_bfe_i32 s8, s28, 0x80000
	s_sext_i32_i16 s8, s8
	s_ashr_i32 s50, s8, 2

; #define PG8_STAGE(bufoff, gbase, voff) do { _Pragma("unroll") for (int _i = 0; _i < 2; ++_i) \
;         __builtin_amdgcn_global_load_lds((const unsigned*)((const char*)(gbase) + (voff)[_i]), (PG8_LAS unsigned*)(lds + (bufoff) + ldsw + _i * 8192), 16, 0, 0); } while (0)
; #define PG8_LDA(dst, b, h) do { _Pragma("unroll") for (int m = 0; m < 4; ++m) _Pragma("unroll") for (int k = 0; k < 2; ++k) dst[m][k] = *(const PG8_LAS bf16x8*)(lds + PG8_SA(b, h) + aoff + m * 2048 + k * 1024); } while (0)
; #define PG8_LDB(dst, b, h) do { _Pragma("unroll") for (int n = 0; n < 2; ++n) _Pragma("unroll") for (int k = 0; k < 2; ++k) dst[n][k] = *(const PG8_LAS bf16x8*)(lds + PG8_SB(b, h) + boff + n * 2048 + k * 1024); } while (0)
; #define PG8_MMA(ai, bj, At, Bt) do { __builtin_amdgcn_s_setprio(1); _Pragma("unroll") for (int m = 0; m < 4; ++m) _Pragma("unroll") for (int n = 0; n < 2; ++n) _Pragma("unroll") for (int k = 0; k < 2; ++k) \
;         acc[ai][bj][m][n] = __builtin_amdgcn_mfma_f32_16x16x32_bf16(Bt[n][k], At[m][k], acc[ai][bj][m][n], 0, 0, 0); __builtin_amdgcn_s_setprio(0); } while (0)
; #define PG8_WAIT_V(n) asm volatile("s_waitcnt vmcnt(" #n ")" ::: "memory")
; #define PG8_WAIT_L(n) asm volatile("s_waitcnt lgkmcnt(" #n ")" ::: "memory")
; #define PG8_BAR __builtin_amdgcn_s_barrier()
; #define PG8_SCHED __builtin_amdgcn_sched_barrier(0)
; template <class Epi, class Sched, bool ALIGN_EPI = false, bool SP2 = false>
; __device__ __forceinline__ void gemm_phase(PG8_LAS unsigned char* lds, const Gemm g, const Sched& S, const Epi& E) {
;     ...
;             PG8_LDB(B0, 0, 0); PG8_LDB(B1, 0, 1); PG8_SCHED; PG8_LDA(At, 0, 0); PG8_STAGE(PG8_SA(1, 1), a1 + hstep, voffA);
;             PG8_WAIT_V(8); PG8_WAIT_L(0); PG8_BAR; PG8_MMA(0, 0, At, B0); PG8_MMA(0, 1, At, B1); PG8_BAR; PG8_SCHED;
;             PG8_LDA(At, 0, 1); PG8_STAGE(PG8_SB(0, 0), b2, voffB); PG8_STAGE(PG8_SB(0, 1), b2 + hstep, voffB); PG8_STAGE(PG8_SA(0, 0), a2, voffA);
;             PG8_WAIT_V(8); PG8_WAIT_L(0); PG8_BAR; PG8_MMA(1, 0, At, B0); PG8_MMA(1, 1, At, B1); PG8_BAR; PG8_SCHED;
;             PG8_LDB(B0, 1, 0); PG8_LDB(B1, 1, 1); PG8_SCHED; PG8_LDA(At, 1, 0); PG8_STAGE(PG8_SA(0, 1), a2 + hstep, voffA);
;             PG8_WAIT_V(8); PG8_WAIT_L(0); PG8_BAR; PG8_MMA(0, 0, At, B0); PG8_MMA(0, 1, At, B1); PG8_BAR; PG8_SCHED;
.Lsp_0:
	s_add_u32 s8, s66, 0xfffc0080
	s_addc_u32 s37, s67, -1
	s_add_i32 s49, 0, 0x10000
	s_cmp_eq_u32 s36, 12
	s_cselect_b32 s65, s28, s37
	s_cselect_b32 s64, s29, s8
	s_cselect_b32 s59, s30, s35
	s_cselect_b32 s58, s31, s34
	s_add_i32 s8, 0, 0x14000
	v_lshl_add_u64 v[208:209], s[66:67], 0, v[136:137]
	s_add_i32 m0, s18, 0xc000
	global_load_lds_dwordx4 v[208:209], off
	v_lshl_add_u64 v[208:209], s[66:67], 0, v[138:139]
	s_add_i32 m0, s18, 0xe000
	s_nop 0
	global_load_lds_dwordx4 v[208:209], off
	s_waitcnt vmcnt(8)
	s_waitcnt lgkmcnt(0)
	s_barrier
	s_waitcnt lgkmcnt(0)
	v_mfma_f32_16x16x32_bf16 v[124:127], v[140:143], v[176:179], 0
	v_mfma_f32_16x16x32_bf16 v[116:119], v[152:155], v[176:179], 0
	v_mfma_f32_16x16x32_bf16 v[108:111], v[140:143], v[184:187], 0
	v_mfma_f32_16x16x32_bf16 v[100:103], v[152:155], v[184:187], 0
	v_mfma_f32_16x16x32_bf16 v[92:95], v[140:143], v[192:195], 0
	v_mfma_f32_16x16x32_bf16 v[84:87], v[152:155], v[192:195], 0
	v_mfma_f32_16x16x32_bf16 v[76:79], v[140:143], v[200:203], 0
	v_mfma_f32_16x16x32_bf16 v[68:71], v[152:155], v[200:203], 0
	v_mfma_f32_16x16x32_bf16 v[124:127], v[148:151], v[180:183], v[124:127]
	v_mfma_f32_16x16x32_bf16 v[116:119], v[156:159], v[180:183], v[116:119]
	v_mfma_f32_16x16x32_bf16 v[108:111], v[148:151], v[188:191], v[108:111]
	v_mfma_f32_16x16x32_bf16 v[100:103], v[156:159], v[188:191], v[100:103]
	v_mfma_f32_16x16x32_bf16 v[92:95], v[148:151], v[196:199], v[92:95]
	v_mfma_f32_16x16x32_bf16 v[84:87], v[156:159], v[196:199], v[84:87]
	v_mfma_f32_16x16x32_bf16 v[76:79], v[148:151], v[204:207], v[76:79]
	v_mfma_f32_16x16x32_bf16 v[68:71], v[156:159], v[204:207], v[68:71]
	v_mfma_f32_16x16x32_bf16 v[120:123], v[160:163], v[176:179], 0
	v_mfma_f32_16x16x32_bf16 v[112:115], v[168:171], v[176:179], 0
	v_mfma_f32_16x16x32_bf16 v[104:107], v[160:163], v[184:187], 0
	v_mfma_f32_16x16x32_bf16 v[96:99], v[168:171], v[184:187], 0
	v_mfma_f32_16x16x32_bf16 v[88:91], v[160:163], v[192:195], 0
	v_mfma_f32_16x16x32_bf16 v[80:83], v[168:171], v[192:195], 0
	v_mfma_f32_16x16x32_bf16 v[72:75], v[160:163], v[200:203], 0
	v_mfma_f32_16x16x32_bf16 v[64:67], v[168:171], v[200:203], 0
	v_mfma_f32_16x16x32_bf16 v[120:123], v[164:167], v[180:183], v[120:123]
	v_mfma_f32_16x16x32_bf16 v[112:115], v[172:175], v[180:183], v[112:115]
	v_mfma_f32_16x16x32_bf16 v[104:107], v[164:167], v[188:191], v[104:107]
	v_mfma_f32_16x16x32_bf16 v[96:99], v[172:175], v[188:191], v[96:99]
	v_mfma_f32_16x16x32_bf16 v[88:91], v[164:167], v[196:199], v[88:91]
	v_mfma_f32_16x16x32_bf16 v[80:83], v[172:175], v[196:199], v[80:83]
	v_mfma_f32_16x16x32_bf16 v[72:75], v[164:167], v[204:207], v[72:75]
	v_mfma_f32_16x16x32_bf16 v[64:67], v[172:175], v[204:207], v[64:67]
	s_barrier
	s_add_i32 s37, s49, s17
	v_lshl_add_u64 v[208:209], s[58:59], 0, v[128:129]
	s_mov_b32 m0, s37
	ds_read_b128 v[176:179], v147 offset:16384
	ds_read_b128 v[180:183], v147 offset:17408
	ds_read_b128 v[184:187], v147 offset:18432
	ds_read_b128 v[188:191], v147 offset:19456
	ds_read_b128 v[192:195], v147 offset:20480
	ds_read_b128 v[196:199], v147 offset:21504
	ds_read_b128 v[200:203], v147 offset:22528
	ds_read_b128 v[204:207], v147 offset:23552
	global_load_lds_dwordx4 v[208:209], off
	s_add_i32 m0, s37, 0x2000
	s_add_u32 s72, s58, 0x40000
	v_lshl_add_u64 v[210:211], s[58:59], 0, v[130:131]
	s_addc_u32 s73, s59, 0
	s_add_i32 s8, s8, s17
	global_load_lds_dwordx4 v[210:211], off
	v_lshl_add_u64 v[214:215], s[72:73], 0, v[128:129]
	s_mov_b32 m0, s8
	v_lshl_add_u64 v[222:223], s[64:65], 0, v[132:133]
	global_load_lds_dwordx4 v[214:215], off
	v_lshl_add_u64 v[214:215], s[72:73], 0, v[130:131]
	s_add_i32 m0, s8, 0x2000
	s_nop 0
	global_load_lds_dwordx4 v[214:215], off
	v_lshl_add_u64 v[214:215], s[64:65], 0, v[134:135]
	s_mov_b32 m0, s18
	s_nop 0
	global_load_lds_dwordx4 v[214:215], off
	s_mov_b32 m0, s19
	s_nop 0
	global_load_lds_dwordx4 v[222:223], off
	s_waitcnt vmcnt(8)
	s_waitcnt lgkmcnt(0)
	s_barrier
	s_waitcnt lgkmcnt(0)
	v_mfma_f32_16x16x32_bf16 v[60:63], v[140:143], v[176:179], 0
	v_mfma_f32_16x16x32_bf16 v[52:55], v[152:155], v[176:179], 0
	v_mfma_f32_16x16x32_bf16 v[44:47], v[140:143], v[184:187], 0
	v_mfma_f32_16x16x32_bf16 v[36:39], v[152:155], v[184:187], 0
	v_mfma_f32_16x16x32_bf16 v[28:31], v[140:143], v[192:195], 0
	v_mfma_f32_16x16x32_bf16 v[20:23], v[152:155], v[192:195], 0
	v_mfma_f32_16x16x32_bf16 v[12:15], v[140:143], v[200:203], 0
	v_mfma_f32_16x16x32_bf16 v[4:7], v[152:155], v[200:203], 0
	v_mfma_f32_16x16x32_bf16 v[60:63], v[148:151], v[180:183], v[60:63]
	v_mfma_f32_16x16x32_bf16 v[52:55], v[156:159], v[180:183], v[52:55]
	v_mfma_f32_16x16x32_bf16 v[44:47], v[148:151], v[188:191], v[44:47]
	v_mfma_f32_16x16x32_bf16 v[36:39], v[156:159], v[188:191], v[36:39]
	v_mfma_f32_16x16x32_bf16 v[28:31], v[148:151], v[196:199], v[28:31]
	v_mfma_f32_16x16x32_bf16 v[20:23], v[156:159], v[196:199], v[20:23]
	v_mfma_f32_16x16x32_bf16 v[12:15], v[148:151], v[204:207], v[12:15]
	v_mfma_f32_16x16x32_bf16 v[4:7], v[156:159], v[204:207], v[4:7]
	v_mfma_f32_16x16x32_bf16 v[56:59], v[160:163], v[176:179], 0
	v_mfma_f32_16x16x32_bf16 v[48:51], v[168:171], v[176:179], 0
	v_mfma_f32_16x16x32_bf16 v[40:43], v[160:163], v[184:187], 0
	v_mfma_f32_16x16x32_bf16 v[32:35], v[168:171], v[184:187], 0
	v_mfma_f32_16x16x32_bf16 v[24:27], v[160:163], v[192:195], 0
	v_mfma_f32_16x16x32_bf16 v[16:19], v[168:171], v[192:195], 0
	v_mfma_f32_16x16x32_bf16 v[8:11], v[160:163], v[200:203], 0
	v_mfma_f32_16x16x32_bf16 v[0:3], v[168:171], v[200:203], 0
	v_mfma_f32_16x16x32_bf16 v[56:59], v[164:167], v[180:183], v[56:59]
	v_mfma_f32_16x16x32_bf16 v[48:51], v[172:175], v[180:183], v[48:51]
	v_mfma_f32_16x16x32_bf16 v[40:43], v[164:167], v[188:191], v[40:43]
	v_mfma_f32_16x16x32_bf16 v[32:35], v[172:175], v[188:191], v[32:35]
	v_mfma_f32_16x16x32_bf16 v[24:27], v[164:167], v[196:199], v[24:27]
	v_mfma_f32_16x16x32_bf16 v[16:19], v[172:175], v[196:199], v[16:19]
	v_mfma_f32_16x16x32_bf16 v[8:11], v[164:167], v[204:207], v[8:11]
	v_mfma_f32_16x16x32_bf16 v[0:3], v[172:175], v[204:207], v[0:3]
	s_barrier
; #define PG8_STAGE(bufoff, gbase, voff) do { _Pragma("unroll") for (int _i = 0; _i < 2; ++_i) \
;         __builtin_amdgcn_global_load_lds((const unsigned*)((const char*)(gbase) + (voff)[_i]), (PG8_LAS unsigned*)(lds + (bufoff) + ldsw + _i * 8192), 16, 0, 0); } while (0)
; #define PG8_LDA(dst, b, h) do { _Pragma("unroll") for (int m = 0; m < 4; ++m) _Pragma("unroll") for (int k = 0; k < 2; ++k) dst[m][k] = *(const PG8_LAS bf16x8*)(lds + PG8_SA(b, h) + aoff + m * 2048 + k * 1024); } while (0)
; #define PG8_LDB(dst, b, h) do { _Pragma("unroll") for (int n = 0; n < 2; ++n) _Pragma("unroll") for (int k = 0; k < 2; ++k) dst[n][k] = *(const PG8_LAS bf16x8*)(lds + PG8_SB(b, h) + boff + n * 2048 + k * 1024); } while (0)
; #define PG8_MMA(ai, bj, At, Bt) do { __builtin_amdgcn_s_setprio(1); _Pragma("unroll") for (int m = 0; m < 4; ++m) _Pragma("unroll") for (int n = 0; n < 2; ++n) _Pragma("unroll") for (int k = 0; k < 2; ++k) \
;         acc[ai][bj][m][n] = __builtin_amdgcn_mfma_f32_16x16x32_bf16(Bt[n][k], At[m][k], acc[ai][bj][m][n], 0, 0, 0); __builtin_amdgcn_s_setprio(0); } while (0)
; #define PG8_WAIT_V(n) asm volatile("s_waitcnt vmcnt(" #n ")" ::: "memory")
; #define PG8_WAIT_L(n) asm volatile("s_waitcnt lgkmcnt(" #n ")" ::: "memory")
; #define PG8_BAR __builtin_amdgcn_s_barrier()
; #define PG8_SCHED __builtin_amdgcn_sched_barrier(0)
; template <class Epi, class Sched, bool ALIGN_EPI = false, bool SP2 = false>
; __device__ __forceinline__ void gemm_phase(PG8_LAS unsigned char* lds, const Gemm g, const Sched& S, const Epi& E) {
;     ...
;         for (int t = 0; t < nt; t += 2) {
;             const bool last = (t == nt - 2);
;     ...
;             PG8_LDB(B0, 1, 0); PG8_LDB(B1, 1, 1); PG8_SCHED; PG8_LDA(At, 1, 0); PG8_STAGE(PG8_SA(0, 1), a2 + hstep, voffA);
;             PG8_WAIT_V(8); PG8_WAIT_L(0); PG8_BAR; PG8_MMA(0, 0, At, B0); PG8_MMA(0, 1, At, B1); PG8_BAR; PG8_SCHED;
;             PG8_LDA(At, 1, 1); PG8_STAGE(PG8_SB(1, 0), b3, voffB); PG8_STAGE(PG8_SB(1, 1), b3 + hstep, voffB); PG8_STAGE(PG8_SA(1, 0), a3, voffA);
;             PG8_WAIT_V(8); PG8_WAIT_L(0); PG8_BAR; PG8_MMA(1, 0, At, B0); PG8_MMA(1, 1, At, B1); PG8_BAR; PG8_SCHED;
	s_add_i32 s8, 0, 0x18000
	s_add_i32 s37, 0, 0x1c000
	v_add_u32_e32 v156, s8, v145
	v_add_u32_e32 v172, s37, v145
	ds_read_b128 v[140:143], v156
	ds_read_b128 v[148:151], v156 offset:1024
	ds_read_b128 v[152:155], v156 offset:2048
	ds_read_b128 v[156:159], v156 offset:3072
	ds_read_b128 v[160:163], v172
	ds_read_b128 v[164:167], v172 offset:1024
	ds_read_b128 v[168:171], v172 offset:2048
	ds_read_b128 v[172:175], v172 offset:3072
	s_add_u32 s64, s64, 0x40000
	s_addc_u32 s65, s65, 0
	s_mov_b32 m0, s20
	v_lshl_add_u64 v[228:229], s[64:65], 0, v[134:135]
	ds_read_b128 v[176:179], v147 offset:32768
	ds_read_b128 v[180:183], v147 offset:33792
	ds_read_b128 v[184:187], v147 offset:34816
	ds_read_b128 v[188:191], v147 offset:35840
	ds_read_b128 v[192:195], v147 offset:36864
	ds_read_b128 v[196:199], v147 offset:37888
	ds_read_b128 v[200:203], v147 offset:38912
	ds_read_b128 v[204:207], v147 offset:39936
	global_load_lds_dwordx4 v[228:229], off
	v_lshl_add_u64 v[228:229], s[64:65], 0, v[132:133]
	s_mov_b32 m0, s21
	s_nop 0
	global_load_lds_dwordx4 v[228:229], off
	s_waitcnt vmcnt(8)
	s_waitcnt lgkmcnt(0)
	s_barrier
	s_waitcnt lgkmcnt(0)
	v_mfma_f32_16x16x32_bf16 v[124:127], v[140:143], v[176:179], v[124:127]
	v_mfma_f32_16x16x32_bf16 v[116:119], v[152:155], v[176:179], v[116:119]
	v_mfma_f32_16x16x32_bf16 v[108:111], v[140:143], v[184:187], v[108:111]
	v_mfma_f32_16x16x32_bf16 v[100:103], v[152:155], v[184:187], v[100:103]
	v_mfma_f32_16x16x32_bf16 v[92:95], v[140:143], v[192:195], v[92:95]
	v_mfma_f32_16x16x32_bf16 v[84:87], v[152:155], v[192:195], v[84:87]
	v_mfma_f32_16x16x32_bf16 v[76:79], v[140:143], v[200:203], v[76:79]
	v_mfma_f32_16x16x32_bf16 v[68:71], v[152:155], v[200:203], v[68:71]
	v_mfma_f32_16x16x32_bf16 v[124:127], v[148:151], v[180:183], v[124:127]
	v_mfma_f32_16x16x32_bf16 v[116:119], v[156:159], v[180:183], v[116:119]
	v_mfma_f32_16x16x32_bf16 v[108:111], v[148:151], v[188:191], v[108:111]
	v_mfma_f32_16x16x32_bf16 v[100:103], v[156:159], v[188:191], v[100:103]
	v_mfma_f32_16x16x32_bf16 v[92:95], v[148:151], v[196:199], v[92:95]
	v_mfma_f32_16x16x32_bf16 v[84:87], v[156:159], v[196:199], v[84:87]
	v_mfma_f32_16x16x32_bf16 v[76:79], v[148:151], v[204:207], v[76:79]
	v_mfma_f32_16x16x32_bf16 v[68:71], v[156:159], v[204:207], v[68:71]
	v_mfma_f32_16x16x32_bf16 v[120:123], v[160:163], v[176:179], v[120:123]
	v_mfma_f32_16x16x32_bf16 v[112:115], v[168:171], v[176:179], v[112:115]
	v_mfma_f32_16x16x32_bf16 v[104:107], v[160:163], v[184:187], v[104:107]
	v_mfma_f32_16x16x32_bf16 v[96:99], v[168:171], v[184:187], v[96:99]
	v_mfma_f32_16x16x32_bf16 v[88:91], v[160:163], v[192:195], v[88:91]
	v_mfma_f32_16x16x32_bf16 v[80:83], v[168:171], v[192:195], v[80:83]
	v_mfma_f32_16x16x32_bf16 v[72:75], v[160:163], v[200:203], v[72:75]
	v_mfma_f32_16x16x32_bf16 v[64:67], v[168:171], v[200:203], v[64:67]
	v_mfma_f32_16x16x32_bf16 v[120:123], v[164:167], v[180:183], v[120:123]
	v_mfma_f32_16x16x32_bf16 v[112:115], v[172:175], v[180:183], v[112:115]
	v_mfma_f32_16x16x32_bf16 v[104:107], v[164:167], v[188:191], v[104:107]
	v_mfma_f32_16x16x32_bf16 v[96:99], v[172:175], v[188:191], v[96:99]
	v_mfma_f32_16x16x32_bf16 v[88:91], v[164:167], v[196:199], v[88:91]
	v_mfma_f32_16x16x32_bf16 v[80:83], v[172:175], v[196:199], v[80:83]
	v_mfma_f32_16x16x32_bf16 v[72:75], v[164:167], v[204:207], v[72:75]
	v_mfma_f32_16x16x32_bf16 v[64:67], v[172:175], v[204:207], v[64:67]
	s_barrier
	s_add_i32 s8, s8, s17
	v_lshl_add_u64 v[208:209], v[208:209], 0, s[90:91]
	s_mov_b32 m0, s8
	ds_read_b128 v[176:179], v147 offset:49152
	ds_read_b128 v[180:183], v147 offset:50176
	ds_read_b128 v[184:187], v147 offset:51200
	ds_read_b128 v[188:191], v147 offset:52224
	ds_read_b128 v[192:195], v147 offset:53248
	ds_read_b128 v[196:199], v147 offset:54272
	ds_read_b128 v[200:203], v147 offset:55296
	ds_read_b128 v[204:207], v147 offset:56320
	global_load_lds_dwordx4 v[208:209], off
	s_add_i32 m0, s8, 0x2000
	s_add_u32 s58, s58, 0x40080
	v_lshl_add_u64 v[208:209], v[210:211], 0, s[90:91]
	s_addc_u32 s59, s59, 0
	s_add_i32 s8, s37, s17
	global_load_lds_dwordx4 v[208:209], off
	v_lshl_add_u64 v[208:209], s[58:59], 0, v[128:129]
	s_mov_b32 m0, s8
	s_nop 0
	global_load_lds_dwordx4 v[208:209], off
	v_lshl_add_u64 v[208:209], s[58:59], 0, v[130:131]
	s_add_i32 m0, s8, 0x2000
	s_nop 0
	global_load_lds_dwordx4 v[208:209], off
	v_lshl_add_u64 v[208:209], v[214:215], 0, s[90:91]
	s_mov_b32 m0, s22
	s_nop 0
	global_load_lds_dwordx4 v[208:209], off
	v_lshl_add_u64 v[208:209], v[222:223], 0, s[90:91]
	s_mov_b32 m0, s23
	s_nop 0
	global_load_lds_dwordx4 v[208:209], off
	s_waitcnt vmcnt(8)
	s_waitcnt lgkmcnt(0)
	s_barrier
	s_waitcnt lgkmcnt(0)
	v_mfma_f32_16x16x32_bf16 v[60:63], v[140:143], v[176:179], v[60:63]
	v_mfma_f32_16x16x32_bf16 v[52:55], v[152:155], v[176:179], v[52:55]
	v_mfma_f32_16x16x32_bf16 v[44:47], v[140:143], v[184:187], v[44:47]
	v_mfma_f32_16x16x32_bf16 v[36:39], v[152:155], v[184:187], v[36:39]
	v_mfma_f32_16x16x32_bf16 v[28:31], v[140:143], v[192:195], v[28:31]
	v_mfma_f32_16x16x32_bf16 v[20:23], v[152:155], v[192:195], v[20:23]
	v_mfma_f32_16x16x32_bf16 v[12:15], v[140:143], v[200:203], v[12:15]
	v_mfma_f32_16x16x32_bf16 v[4:7], v[152:155], v[200:203], v[4:7]
	v_mfma_f32_16x16x32_bf16 v[60:63], v[148:151], v[180:183], v[60:63]
	v_mfma_f32_16x16x32_bf16 v[52:55], v[156:159], v[180:183], v[52:55]
	v_mfma_f32_16x16x32_bf16 v[44:47], v[148:151], v[188:191], v[44:47]
	v_mfma_f32_16x16x32_bf16 v[36:39], v[156:159], v[188:191], v[36:39]
	v_mfma_f32_16x16x32_bf16 v[28:31], v[148:151], v[196:199], v[28:31]
	v_mfma_f32_16x16x32_bf16 v[20:23], v[156:159], v[196:199], v[20:23]
	v_mfma_f32_16x16x32_bf16 v[12:15], v[148:151], v[204:207], v[12:15]
	v_mfma_f32_16x16x32_bf16 v[4:7], v[156:159], v[204:207], v[4:7]
	v_mfma_f32_16x16x32_bf16 v[56:59], v[160:163], v[176:179], v[56:59]
	v_mfma_f32_16x16x32_bf16 v[48:51], v[168:171], v[176:179], v[48:51]
	v_mfma_f32_16x16x32_bf16 v[40:43], v[160:163], v[184:187], v[40:43]
	v_mfma_f32_16x16x32_bf16 v[32:35], v[168:171], v[184:187], v[32:35]
	v_mfma_f32_16x16x32_bf16 v[24:27], v[160:163], v[192:195], v[24:27]
	v_mfma_f32_16x16x32_bf16 v[16:19], v[168:171], v[192:195], v[16:19]
	v_mfma_f32_16x16x32_bf16 v[8:11], v[160:163], v[200:203], v[8:11]
	v_mfma_f32_16x16x32_bf16 v[0:3], v[168:171], v[200:203], v[0:3]
	v_mfma_f32_16x16x32_bf16 v[56:59], v[164:167], v[180:183], v[56:59]
	v_mfma_f32_16x16x32_bf16 v[48:51], v[172:175], v[180:183], v[48:51]
	v_mfma_f32_16x16x32_bf16 v[40:43], v[164:167], v[188:191], v[40:43]
	v_mfma_f32_16x16x32_bf16 v[32:35], v[172:175], v[188:191], v[32:35]
	v_mfma_f32_16x16x32_bf16 v[24:27], v[164:167], v[196:199], v[24:27]
	v_mfma_f32_16x16x32_bf16 v[16:19], v[172:175], v[196:199], v[16:19]
	v_mfma_f32_16x16x32_bf16 v[8:11], v[164:167], v[204:207], v[8:11]
	v_mfma_f32_16x16x32_bf16 v[0:3], v[172:175], v[204:207], v[0:3]
	s_barrier
	s_add_i32 s36, s36, 2
	s_add_u32 s66, s66, 0x100
	s_addc_u32 s67, s67, 0
	s_add_u32 s34, s34, 0x100
	s_addc_u32 s35, s35, 0
	s_cmp_gt_u32 s36, 13
	s_cbranch_scc1 .Lpeel_x0
